# W2A weight-conversion loop software-pipelined (next tile loads issued before converting the current tile)
# baseline (speedup 1.0000x reference)
.LBB0_1140:
	s_waitcnt vmcnt(15)
	ds_write2_b32 v81, v62, v63 offset1:1
	ds_write2_b32 v81, v64, v65 offset0:2 offset1:3
	v_add_u32_e32 v62, 0x410, v81
	s_waitcnt vmcnt(14)
	ds_write2_b32 v62, v50, v51 offset1:1
	v_add_u32_e32 v50, 0x418, v81
	ds_write2_b32 v50, v52, v53 offset1:1
	v_add_u32_e32 v50, 0x820, v81
	s_waitcnt vmcnt(13)
	ds_write2_b32 v50, v58, v59 offset1:1
	v_add_u32_e32 v50, 0x828, v81
	ds_write2_b32 v50, v60, v61 offset1:1
	v_add_u32_e32 v50, 0xc30, v81
	s_waitcnt vmcnt(12)
	ds_write2_b32 v50, v42, v43 offset1:1
	v_add_u32_e32 v42, 0xc38, v81
	ds_write2_b32 v42, v44, v45 offset1:1
	v_add_u32_e32 v42, 0x1040, v81
	s_waitcnt vmcnt(11)
	ds_write2_b32 v42, v54, v55 offset1:1
	v_add_u32_e32 v42, 0x1048, v81
	ds_write2_b32 v42, v56, v57 offset1:1
	v_add_u32_e32 v42, 0x1450, v81
	s_waitcnt vmcnt(10)
	ds_write2_b32 v42, v34, v35 offset1:1
	v_add_u32_e32 v34, 0x1458, v81
	ds_write2_b32 v34, v36, v37 offset1:1
	v_add_u32_e32 v34, 0x1860, v81
	s_waitcnt vmcnt(9)
	ds_write2_b32 v34, v46, v47 offset1:1
	v_add_u32_e32 v34, 0x1868, v81
	ds_write2_b32 v34, v48, v49 offset1:1
	v_add_u32_e32 v34, 0x1c70, v81
	s_waitcnt vmcnt(8)
	ds_write2_b32 v34, v26, v27 offset1:1
	v_add_u32_e32 v26, 0x1c78, v81
	ds_write2_b32 v26, v28, v29 offset1:1
	v_add_u32_e32 v26, 0x2080, v81
	s_waitcnt vmcnt(7)
	ds_write2_b32 v26, v38, v39 offset1:1
	v_add_u32_e32 v26, 0x2088, v81
	ds_write2_b32 v26, v40, v41 offset1:1
	v_add_u32_e32 v26, 0x2490, v81
	s_waitcnt vmcnt(6)
	ds_write2_b32 v26, v18, v19 offset1:1
	v_add_u32_e32 v18, 0x2498, v81
	ds_write2_b32 v18, v20, v21 offset1:1
	v_add_u32_e32 v18, 0x28a0, v81
	s_waitcnt vmcnt(5)
	ds_write2_b32 v18, v30, v31 offset1:1
	v_add_u32_e32 v18, 0x28a8, v81
	ds_write2_b32 v18, v32, v33 offset1:1
	v_add_u32_e32 v18, 0x2cb0, v81
	s_waitcnt vmcnt(4)
	ds_write2_b32 v18, v10, v11 offset1:1
	v_add_u32_e32 v10, 0x2cb8, v81
	ds_write2_b32 v10, v12, v13 offset1:1
	v_add_u32_e32 v10, 0x30c0, v81
	s_waitcnt vmcnt(3)
	ds_write2_b32 v10, v22, v23 offset1:1
	v_add_u32_e32 v10, 0x30c8, v81
	ds_write2_b32 v10, v24, v25 offset1:1
	v_add_u32_e32 v10, 0x34d0, v81
	s_waitcnt vmcnt(2)
	ds_write2_b32 v10, v6, v7 offset1:1
	v_add_u32_e32 v6, 0x34d8, v81
	ds_write2_b32 v6, v8, v9 offset1:1
	v_add_u32_e32 v6, 0x38e0, v81
	s_waitcnt vmcnt(1)
	ds_write2_b32 v6, v14, v15 offset1:1
	v_add_u32_e32 v6, 0x38e8, v81
	s_mulk_i32 s1, 0xfea8
	ds_write2_b32 v6, v16, v17 offset1:1
	v_add_u32_e32 v6, 0x3cf0, v81
	s_add_i32 s1, s7, s1
	s_add_i32 s5, s4, 0xffffd500
	s_waitcnt vmcnt(0)
	ds_write2_b32 v6, v2, v3 offset1:1
	v_add_u32_e32 v2, 0x3cf8, v81
	s_cmpk_lt_i32 s1, 0xac
	ds_write2_b32 v2, v4, v5 offset1:1
	s_cselect_b32 s1, s4, s5
	s_waitcnt lgkmcnt(0)
	s_cselect_b32 s4, 0, 0x80
	s_lshl_b32 s5, s1, 1
	s_and_b32 s1, s1, 64
	s_and_b32 s5, s5, 0xffffff00
	s_or_b32 s1, s1, s4
	s_mov_b32 s98, s0
	s_mov_b32 s99, s1
	s_mov_b32 s100, s5
	s_add_i32 s7, s7, s6
	s_add_i32 s8, s8, s9
	s_cmpk_gt_i32 s7, 0x55ff
	s_cselect_b32 s101, 0, 1
	s_cbranch_scc1 .Lpipe_w2a_nonext
	s_mul_hi_i32 s0, s7, 0x2fa0be83
	s_lshr_b32 s1, s0, 31
	s_ashr_i32 s0, s0, 6
	s_add_i32 s1, s0, s1
	s_mul_i32 s0, s1, 0xffffaa00
	s_add_i32 s4, s8, s0
	s_lshl_b32 s0, s1, 6
	v_or_b32_e32 v70, s0, v204
	s_ashr_i32 s5, s4, 31
	v_lshl_add_u64 v[2:3], s[4:5], 2, v[66:67]
	v_or_b32_e32 v6, 4, v70
	v_mad_i64_i32 v[4:5], s[12:13], v70, s10, v[2:3]
	v_mad_i64_i32 v[6:7], s[12:13], v6, s10, v[2:3]
	global_load_dwordx4 v[62:65], v[4:5], off
	global_load_dwordx4 v[50:53], v[6:7], off
	v_or_b32_e32 v4, 8, v70
	v_or_b32_e32 v6, 12, v70
	v_mad_i64_i32 v[4:5], s[12:13], v4, s10, v[2:3]
	v_mad_i64_i32 v[6:7], s[12:13], v6, s10, v[2:3]
	global_load_dwordx4 v[58:61], v[4:5], off
	global_load_dwordx4 v[42:45], v[6:7], off
	v_or_b32_e32 v4, 16, v70
	v_or_b32_e32 v6, 20, v70
	v_mad_i64_i32 v[4:5], s[12:13], v4, s10, v[2:3]
	v_mad_i64_i32 v[6:7], s[12:13], v6, s10, v[2:3]
	global_load_dwordx4 v[54:57], v[4:5], off
	global_load_dwordx4 v[34:37], v[6:7], off
	v_or_b32_e32 v4, 24, v70
	v_or_b32_e32 v6, 28, v70
	v_mad_i64_i32 v[4:5], s[12:13], v4, s10, v[2:3]
	v_mad_i64_i32 v[6:7], s[12:13], v6, s10, v[2:3]
	global_load_dwordx4 v[46:49], v[4:5], off
	global_load_dwordx4 v[26:29], v[6:7], off
	v_or_b32_e32 v4, 32, v70
	v_or_b32_e32 v6, 36, v70
	v_mad_i64_i32 v[4:5], s[12:13], v4, s10, v[2:3]
	v_mad_i64_i32 v[6:7], s[12:13], v6, s10, v[2:3]
	global_load_dwordx4 v[38:41], v[4:5], off
	global_load_dwordx4 v[18:21], v[6:7], off
	v_or_b32_e32 v4, 40, v70
	v_or_b32_e32 v6, 44, v70
	v_mad_i64_i32 v[4:5], s[12:13], v4, s10, v[2:3]
	v_mad_i64_i32 v[6:7], s[12:13], v6, s10, v[2:3]
	global_load_dwordx4 v[30:33], v[4:5], off
	global_load_dwordx4 v[10:13], v[6:7], off
	v_or_b32_e32 v4, 48, v70
	v_or_b32_e32 v6, 52, v70
	v_mad_i64_i32 v[4:5], s[12:13], v4, s10, v[2:3]
	v_mad_i64_i32 v[6:7], s[12:13], v6, s10, v[2:3]
	global_load_dwordx4 v[22:25], v[4:5], off
	s_nop 0
	global_load_dwordx4 v[6:9], v[6:7], off
	v_or_b32_e32 v4, 56, v70
	v_or_b32_e32 v14, 60, v70
	v_mad_i64_i32 v[4:5], s[12:13], v4, s10, v[2:3]
	v_mad_i64_i32 v[2:3], s[12:13], v14, s10, v[2:3]
	global_load_dwordx4 v[14:17], v[4:5], off
	s_nop 0
	global_load_dwordx4 v[2:5], v[2:3], off
.Lpipe_w2a_nonext:
	v_add_u32_e32 v230, 0x400, v73
	ds_read2_b32 v[210:211], v73 offset0:65 offset1:73
	ds_read2_b32 v[212:213], v73 offset1:8
	ds_read2_b32 v[214:215], v73 offset0:130 offset1:138
	ds_read2_b32 v[216:217], v73 offset0:195 offset1:203
	ds_read2_b32 v[218:219], v230 offset0:4 offset1:12
	ds_read2_b32 v[220:221], v230 offset0:69 offset1:77
	ds_read2_b32 v[222:223], v230 offset0:134 offset1:142
	ds_read2_b32 v[224:225], v230 offset0:199 offset1:207
	s_or_b32 s100, s99, s100
	v_or_b32_e32 v228, s100, v72
	s_ashr_i32 s99, s98, 31
	v_ashrrev_i32_e32 v229, 31, v228
	v_lshl_add_u64 v[226:227], s[98:99], 1, v[68:69]
	v_lshlrev_b64 v[228:229], 13, v[228:229]
	s_waitcnt lgkmcnt(6)
	v_cvt_pk_bf16_f32 v206, v212, v210
	s_waitcnt lgkmcnt(4)
	v_cvt_pk_bf16_f32 v207, v214, v216
	s_waitcnt lgkmcnt(2)
	v_cvt_pk_bf16_f32 v208, v218, v220
	s_waitcnt lgkmcnt(0)
	v_cvt_pk_bf16_f32 v209, v222, v224
	v_lshl_add_u64 v[228:229], v[226:227], 0, v[228:229]
	v_or_b32_e32 v210, s100, v74
	global_store_dwordx4 v[228:229], v[206:209], off
	s_nop 0
	s_nop 0
	v_cvt_pk_bf16_f32 v206, v213, v211
	v_ashrrev_i32_e32 v211, 31, v210
	v_cvt_pk_bf16_f32 v207, v215, v217
	v_cvt_pk_bf16_f32 v208, v219, v221
	v_cvt_pk_bf16_f32 v209, v223, v225
	v_lshlrev_b64 v[210:211], 13, v[210:211]
	ds_read2_b32 v[212:213], v73 offset0:81 offset1:89
	ds_read2_b32 v[214:215], v73 offset0:16 offset1:24
	ds_read2_b32 v[216:217], v73 offset0:146 offset1:154
	ds_read2_b32 v[218:219], v73 offset0:211 offset1:219
	ds_read2_b32 v[220:221], v230 offset0:20 offset1:28
	ds_read2_b32 v[222:223], v230 offset0:85 offset1:93
	ds_read2_b32 v[224:225], v230 offset0:150 offset1:158
	ds_read2_b32 v[228:229], v230 offset0:215 offset1:223
	v_lshl_add_u64 v[210:211], v[226:227], 0, v[210:211]
	global_store_dwordx4 v[210:211], v[206:209], off
	v_or_b32_e32 v210, s100, v75
	v_ashrrev_i32_e32 v211, 31, v210
	v_lshlrev_b64 v[210:211], 13, v[210:211]
	s_waitcnt lgkmcnt(6)
	v_cvt_pk_bf16_f32 v206, v214, v212
	s_waitcnt lgkmcnt(4)
	v_cvt_pk_bf16_f32 v207, v216, v218
	s_waitcnt lgkmcnt(2)
	v_cvt_pk_bf16_f32 v208, v220, v222
	s_waitcnt lgkmcnt(0)
	v_cvt_pk_bf16_f32 v209, v224, v228
	v_lshl_add_u64 v[210:211], v[226:227], 0, v[210:211]
	global_store_dwordx4 v[210:211], v[206:209], off
	v_or_b32_e32 v210, s100, v76
	v_ashrrev_i32_e32 v211, 31, v210
	v_cvt_pk_bf16_f32 v206, v215, v213
	v_cvt_pk_bf16_f32 v207, v217, v219
	v_cvt_pk_bf16_f32 v208, v221, v223
	v_cvt_pk_bf16_f32 v209, v225, v229
	v_lshlrev_b64 v[210:211], 13, v[210:211]
	ds_read2_b32 v[212:213], v73 offset0:32 offset1:40
	ds_read2_b32 v[214:215], v73 offset0:97 offset1:105
	ds_read2_b32 v[216:217], v73 offset0:162 offset1:170
	ds_read2_b32 v[218:219], v73 offset0:227 offset1:235
	ds_read2_b32 v[220:221], v230 offset0:36 offset1:44
	ds_read2_b32 v[222:223], v230 offset0:101 offset1:109
	ds_read2_b32 v[224:225], v230 offset0:166 offset1:174
	ds_read2_b32 v[228:229], v230 offset0:231 offset1:239
	v_lshl_add_u64 v[210:211], v[226:227], 0, v[210:211]
	global_store_dwordx4 v[210:211], v[206:209], off
	v_or_b32_e32 v210, s100, v77
	v_ashrrev_i32_e32 v211, 31, v210
	v_lshlrev_b64 v[210:211], 13, v[210:211]
	s_waitcnt lgkmcnt(6)
	v_cvt_pk_bf16_f32 v206, v212, v214
	s_waitcnt lgkmcnt(4)
	v_cvt_pk_bf16_f32 v207, v216, v218
	s_waitcnt lgkmcnt(2)
	v_cvt_pk_bf16_f32 v208, v220, v222
	s_waitcnt lgkmcnt(0)
	v_cvt_pk_bf16_f32 v209, v224, v228
	v_lshl_add_u64 v[210:211], v[226:227], 0, v[210:211]
	global_store_dwordx4 v[210:211], v[206:209], off
	v_or_b32_e32 v210, s100, v78
	v_ashrrev_i32_e32 v211, 31, v210
	v_cvt_pk_bf16_f32 v206, v213, v215
	v_cvt_pk_bf16_f32 v207, v217, v219
	v_cvt_pk_bf16_f32 v208, v221, v223
	v_cvt_pk_bf16_f32 v209, v225, v229
	v_lshlrev_b64 v[210:211], 13, v[210:211]
	ds_read2_b32 v[212:213], v73 offset0:48 offset1:56
	ds_read2_b32 v[214:215], v73 offset0:113 offset1:121
	ds_read2_b32 v[216:217], v73 offset0:178 offset1:186
	ds_read2_b32 v[218:219], v73 offset0:243 offset1:251
	ds_read2_b32 v[220:221], v230 offset0:52 offset1:60
	ds_read2_b32 v[222:223], v230 offset0:117 offset1:125
	ds_read2_b32 v[224:225], v230 offset0:182 offset1:190
	ds_read2_b32 v[228:229], v230 offset0:247 offset1:255
	v_lshl_add_u64 v[210:211], v[226:227], 0, v[210:211]
	global_store_dwordx4 v[210:211], v[206:209], off
	v_or_b32_e32 v210, s100, v79
	v_ashrrev_i32_e32 v211, 31, v210
	v_lshlrev_b64 v[210:211], 13, v[210:211]
	s_waitcnt lgkmcnt(6)
	v_cvt_pk_bf16_f32 v206, v212, v214
	s_waitcnt lgkmcnt(4)
	v_cvt_pk_bf16_f32 v207, v216, v218
	s_waitcnt lgkmcnt(2)
	v_cvt_pk_bf16_f32 v208, v220, v222
	s_waitcnt lgkmcnt(0)
	v_cvt_pk_bf16_f32 v209, v224, v228
	v_lshl_add_u64 v[210:211], v[226:227], 0, v[210:211]
	global_store_dwordx4 v[210:211], v[206:209], off
	v_or_b32_e32 v210, s100, v80
	v_ashrrev_i32_e32 v211, 31, v210
	v_lshlrev_b64 v[210:211], 13, v[210:211]
	v_cvt_pk_bf16_f32 v206, v213, v215
	v_cvt_pk_bf16_f32 v207, v217, v219
	v_cvt_pk_bf16_f32 v208, v221, v223
	v_cvt_pk_bf16_f32 v209, v225, v229
	v_lshl_add_u64 v[210:211], v[226:227], 0, v[210:211]
	global_store_dwordx4 v[210:211], v[206:209], off
	s_waitcnt lgkmcnt(0)
	s_cmp_lg_u32 s101, 0
	s_cbranch_scc0 .LBB0_1143
	s_branch .Lpipe_w2a_gk

.Lpipe_w2a_gk:
	s_and_b64 vcc, exec, s[2:3]
	s_cbranch_vccnz .LBB0_1140
	v_readlane_b32 s72, v254, 44
	v_ashrrev_i32_e32 v71, 31, v70
	v_readlane_b32 s86, v254, 58
	v_readlane_b32 s87, v254, 59
	v_readlane_b32 s73, v254, 45
	v_readlane_b32 s74, v254, 46
	v_lshl_add_u64 v[70:71], v[70:71], 2, s[86:87]
	global_load_dword v82, v[70:71], off
	global_load_dword v84, v[70:71], off offset:16
	global_load_dword v86, v[70:71], off offset:32
	global_load_dword v88, v[70:71], off offset:48
	global_load_dword v90, v[70:71], off offset:64
	global_load_dword v92, v[70:71], off offset:80
	global_load_dword v94, v[70:71], off offset:96
	global_load_dword v96, v[70:71], off offset:112
	global_load_dword v98, v[70:71], off offset:128
	global_load_dword v100, v[70:71], off offset:144
	global_load_dword v102, v[70:71], off offset:160
	global_load_dword v104, v[70:71], off offset:176
	global_load_dword v106, v[70:71], off offset:192
	global_load_dword v108, v[70:71], off offset:208
	global_load_dword v110, v[70:71], off offset:224
	s_nop 0
	global_load_dword v70, v[70:71], off offset:240
	v_readlane_b32 s75, v254, 47
	v_readlane_b32 s76, v254, 48
	v_readlane_b32 s77, v254, 49
	v_readlane_b32 s78, v254, 50
	v_readlane_b32 s79, v254, 51
	v_readlane_b32 s80, v254, 52
	v_readlane_b32 s81, v254, 53
	v_readlane_b32 s82, v254, 54
	v_readlane_b32 s83, v254, 55
	v_readlane_b32 s84, v254, 56
	v_readlane_b32 s85, v254, 57
	s_waitcnt vmcnt(15)
	v_pk_mul_f32 v[64:65], v[64:65], v[82:83] op_sel_hi:[1,0]
	v_pk_mul_f32 v[62:63], v[62:63], v[82:83] op_sel_hi:[1,0]
	s_waitcnt vmcnt(14)
	v_pk_mul_f32 v[52:53], v[52:53], v[84:85] op_sel_hi:[1,0]
	v_pk_mul_f32 v[50:51], v[50:51], v[84:85] op_sel_hi:[1,0]
	s_waitcnt vmcnt(13)
	v_pk_mul_f32 v[60:61], v[60:61], v[86:87] op_sel_hi:[1,0]
	v_pk_mul_f32 v[58:59], v[58:59], v[86:87] op_sel_hi:[1,0]
	s_waitcnt vmcnt(12)
	v_pk_mul_f32 v[44:45], v[44:45], v[88:89] op_sel_hi:[1,0]
	v_pk_mul_f32 v[42:43], v[42:43], v[88:89] op_sel_hi:[1,0]
	s_waitcnt vmcnt(11)
	v_pk_mul_f32 v[56:57], v[56:57], v[90:91] op_sel_hi:[1,0]
	v_pk_mul_f32 v[54:55], v[54:55], v[90:91] op_sel_hi:[1,0]
	s_waitcnt vmcnt(10)
	v_pk_mul_f32 v[36:37], v[36:37], v[92:93] op_sel_hi:[1,0]
	v_pk_mul_f32 v[34:35], v[34:35], v[92:93] op_sel_hi:[1,0]
	s_waitcnt vmcnt(9)
	v_pk_mul_f32 v[48:49], v[48:49], v[94:95] op_sel_hi:[1,0]
	v_pk_mul_f32 v[46:47], v[46:47], v[94:95] op_sel_hi:[1,0]
	s_waitcnt vmcnt(8)
	v_pk_mul_f32 v[28:29], v[28:29], v[96:97] op_sel_hi:[1,0]
	v_pk_mul_f32 v[26:27], v[26:27], v[96:97] op_sel_hi:[1,0]
	s_waitcnt vmcnt(7)
	v_pk_mul_f32 v[40:41], v[40:41], v[98:99] op_sel_hi:[1,0]
	v_pk_mul_f32 v[38:39], v[38:39], v[98:99] op_sel_hi:[1,0]
	s_waitcnt vmcnt(6)
	v_pk_mul_f32 v[20:21], v[20:21], v[100:101] op_sel_hi:[1,0]
	v_pk_mul_f32 v[18:19], v[18:19], v[100:101] op_sel_hi:[1,0]
	s_waitcnt vmcnt(5)
	v_pk_mul_f32 v[32:33], v[32:33], v[102:103] op_sel_hi:[1,0]
	v_pk_mul_f32 v[30:31], v[30:31], v[102:103] op_sel_hi:[1,0]
	s_waitcnt vmcnt(4)
	v_pk_mul_f32 v[12:13], v[12:13], v[104:105] op_sel_hi:[1,0]
	v_pk_mul_f32 v[10:11], v[10:11], v[104:105] op_sel_hi:[1,0]
	s_waitcnt vmcnt(3)
	v_pk_mul_f32 v[24:25], v[24:25], v[106:107] op_sel_hi:[1,0]
	v_pk_mul_f32 v[22:23], v[22:23], v[106:107] op_sel_hi:[1,0]
	s_waitcnt vmcnt(2)
	v_pk_mul_f32 v[8:9], v[8:9], v[108:109] op_sel_hi:[1,0]
	v_pk_mul_f32 v[6:7], v[6:7], v[108:109] op_sel_hi:[1,0]
	s_waitcnt vmcnt(1)
	v_pk_mul_f32 v[16:17], v[16:17], v[110:111] op_sel_hi:[1,0]
	v_pk_mul_f32 v[14:15], v[14:15], v[110:111] op_sel_hi:[1,0]
	s_waitcnt vmcnt(0)
	v_pk_mul_f32 v[4:5], v[4:5], v[70:71] op_sel_hi:[1,0]
	v_pk_mul_f32 v[2:3], v[2:3], v[70:71] op_sel_hi:[1,0]
	s_branch .LBB0_1140

	.amdhsa_kernel _Z6mk_fwd4Args
		.amdhsa_group_segment_fixed_size 0
		.amdhsa_private_segment_fixed_size 0
		.amdhsa_kernarg_size 568
		.amdhsa_user_sgpr_count 2
		.amdhsa_user_sgpr_dispatch_ptr 0
		.amdhsa_user_sgpr_queue_ptr 0
		.amdhsa_user_sgpr_kernarg_segment_ptr 1
		.amdhsa_user_sgpr_dispatch_id 0
		.amdhsa_user_sgpr_kernarg_preload_length 0
		.amdhsa_user_sgpr_kernarg_preload_offset 0
		.amdhsa_user_sgpr_private_segment_size 0
		.amdhsa_uses_dynamic_stack 0
		.amdhsa_enable_private_segment 0
		.amdhsa_system_sgpr_workgroup_id_x 1
		.amdhsa_system_sgpr_workgroup_id_y 0
		.amdhsa_system_sgpr_workgroup_id_z 0
		.amdhsa_system_sgpr_workgroup_info 0
		.amdhsa_system_vgpr_workitem_id 0
		.amdhsa_next_free_vgpr 256
		.amdhsa_next_free_sgpr 102
		.amdhsa_accum_offset 256
		.amdhsa_reserve_vcc 1
		.amdhsa_float_round_mode_32 0
		.amdhsa_float_round_mode_16_64 0
		.amdhsa_float_denorm_mode_32 3
		.amdhsa_float_denorm_mode_16_64 3
		.amdhsa_dx10_clamp 1
		.amdhsa_ieee_mode 1
		.amdhsa_fp16_overflow 0
		.amdhsa_tg_split 0
		.amdhsa_exception_fp_ieee_invalid_op 0
		.amdhsa_exception_fp_denorm_src 0
		.amdhsa_exception_fp_ieee_div_zero 0
		.amdhsa_exception_fp_ieee_overflow 0
		.amdhsa_exception_fp_ieee_underflow 0
		.amdhsa_exception_fp_ieee_inexact 0
		.amdhsa_exception_int_div_zero 0
	.end_amdhsa_kernel

amdhsa.kernels:
  - .agpr_count:     0
    .args:
      - .offset:         0
        .size:           312
        .value_kind:     by_value
      - .offset:         312
        .size:           4
        .value_kind:     hidden_block_count_x
      - .offset:         316
        .size:           4
        .value_kind:     hidden_block_count_y
      - .offset:         320
        .size:           4
        .value_kind:     hidden_block_count_z
      - .offset:         324
        .size:           2
        .value_kind:     hidden_group_size_x
      - .offset:         326
        .size:           2
        .value_kind:     hidden_group_size_y
      - .offset:         328
        .size:           2
        .value_kind:     hidden_group_size_z
      - .offset:         330
        .size:           2
        .value_kind:     hidden_remainder_x
      - .offset:         332
        .size:           2
        .value_kind:     hidden_remainder_y
      - .offset:         334
        .size:           2
        .value_kind:     hidden_remainder_z
      - .offset:         352
        .size:           8
        .value_kind:     hidden_global_offset_x
      - .offset:         360
        .size:           8
        .value_kind:     hidden_global_offset_y
      - .offset:         368
        .size:           8
        .value_kind:     hidden_global_offset_z
      - .offset:         376
        .size:           2
        .value_kind:     hidden_grid_dims
      - .offset:         432
        .size:           4
        .value_kind:     hidden_dynamic_lds_size
    .group_segment_fixed_size: 0
    .kernarg_segment_align: 8
    .kernarg_segment_size: 568
    .language:       OpenCL C
    .language_version:
      - 2
      - 0
    .max_flat_workgroup_size: 512
    .name:           _Z6mk_fwd4Args
    .private_segment_fixed_size: 0
    .sgpr_count:     108
    .sgpr_spill_count: 108
    .symbol:         _Z6mk_fwd4Args.kd
    .uniform_work_group_size: 1
    .uses_dynamic_stack: false
    .vgpr_count:     256
    .vgpr_spill_count: 0
    .wavefront_size: 64
